# v34 + P2's last (fp8) tile touches the f32 weights the P4 copy reads first (W_mlp_in[0:48MiB), then W_out) with one dummy load per K-loop iteration
# baseline (speedup 1.0000x reference)
.LBB0_377:
	s_ashr_i32 s69, s68, 31
	s_lshl_b64 s[74:75], s[68:69], 19
	s_add_u32 s74, s3, s74
	s_addc_u32 s75, s16, s75
	s_and_b64 s[76:77], s[4:5], exec
	s_cselect_b32 s69, s75, s87
	s_cselect_b32 s83, s74, s86
	s_ashr_i32 s21, s20, 31
	s_lshl_b64 s[76:77], s[20:21], 19
	s_add_u32 s76, s17, s76
	s_addc_u32 s77, s18, s77
	s_and_b64 s[90:91], s[4:5], exec
	s_cselect_b32 s21, s77, s89
	s_cselect_b32 s93, s76, s88
	s_add_u32 s86, s86, 0x40080
	s_addc_u32 s87, s87, 0
	s_add_u32 s94, s88, 0x100
	v_mov_b32_e32 v32, 0
	s_addc_u32 s95, s89, 0
	s_mov_b32 s96, -2
	v_mov_b32_e32 v33, v32
	v_mov_b32_e32 v34, v32
	v_mov_b32_e32 v35, v32
	v_mov_b32_e32 v36, v32
	v_mov_b32_e32 v37, v32
	v_mov_b32_e32 v38, v32
	v_mov_b32_e32 v39, v32
	v_mov_b32_e32 v48, v32
	v_mov_b32_e32 v49, v32
	v_mov_b32_e32 v50, v32
	v_mov_b32_e32 v51, v32
	v_mov_b32_e32 v52, v32
	v_mov_b32_e32 v53, v32
	v_mov_b32_e32 v54, v32
	v_mov_b32_e32 v55, v32
	v_mov_b32_e32 v64, v32
	v_mov_b32_e32 v65, v32
	v_mov_b32_e32 v66, v32
	v_mov_b32_e32 v67, v32
	v_mov_b32_e32 v68, v32
	v_mov_b32_e32 v69, v32
	v_mov_b32_e32 v70, v32
	v_mov_b32_e32 v71, v32
	v_mov_b32_e32 v80, v32
	v_mov_b32_e32 v81, v32
	v_mov_b32_e32 v82, v32
	v_mov_b32_e32 v83, v32
	v_mov_b32_e32 v84, v32
	v_mov_b32_e32 v85, v32
	v_mov_b32_e32 v86, v32
	v_mov_b32_e32 v87, v32
	v_mov_b32_e32 v40, v32
	v_mov_b32_e32 v41, v32
	v_mov_b32_e32 v42, v32
	v_mov_b32_e32 v43, v32
	v_mov_b32_e32 v44, v32
	v_mov_b32_e32 v45, v32
	v_mov_b32_e32 v46, v32
	v_mov_b32_e32 v47, v32
	v_mov_b32_e32 v56, v32
	v_mov_b32_e32 v57, v32
	v_mov_b32_e32 v58, v32
	v_mov_b32_e32 v59, v32
	v_mov_b32_e32 v60, v32
	v_mov_b32_e32 v61, v32
	v_mov_b32_e32 v62, v32
	v_mov_b32_e32 v63, v32
	v_mov_b32_e32 v72, v32
	v_mov_b32_e32 v73, v32
	v_mov_b32_e32 v74, v32
	v_mov_b32_e32 v75, v32
	v_mov_b32_e32 v76, v32
	v_mov_b32_e32 v77, v32
	v_mov_b32_e32 v78, v32
	v_mov_b32_e32 v79, v32
	v_mov_b32_e32 v88, v32
	v_mov_b32_e32 v89, v32
	v_mov_b32_e32 v90, v32
	v_mov_b32_e32 v91, v32
	v_mov_b32_e32 v92, v32
	v_mov_b32_e32 v93, v32
	v_mov_b32_e32 v94, v32
	v_mov_b32_e32 v95, v32
	v_mov_b32_e32 v96, v32
	v_mov_b32_e32 v97, v32
	v_mov_b32_e32 v98, v32
	v_mov_b32_e32 v99, v32
	v_mov_b32_e32 v100, v32
	v_mov_b32_e32 v101, v32
	v_mov_b32_e32 v102, v32
	v_mov_b32_e32 v103, v32
	v_mov_b32_e32 v112, v32
	v_mov_b32_e32 v113, v32
	v_mov_b32_e32 v114, v32
	v_mov_b32_e32 v115, v32
	v_mov_b32_e32 v116, v32
	v_mov_b32_e32 v117, v32
	v_mov_b32_e32 v118, v32
	v_mov_b32_e32 v119, v32
	v_mov_b32_e32 v128, v32
	v_mov_b32_e32 v129, v32
	v_mov_b32_e32 v130, v32
	v_mov_b32_e32 v131, v32
	v_mov_b32_e32 v132, v32
	v_mov_b32_e32 v133, v32
	v_mov_b32_e32 v134, v32
	v_mov_b32_e32 v135, v32
	v_mov_b32_e32 v144, v32
	v_mov_b32_e32 v145, v32
	v_mov_b32_e32 v146, v32
	v_mov_b32_e32 v147, v32
	v_mov_b32_e32 v148, v32
	v_mov_b32_e32 v149, v32
	v_mov_b32_e32 v150, v32
	v_mov_b32_e32 v151, v32
	v_mov_b32_e32 v104, v32
	v_mov_b32_e32 v105, v32
	v_mov_b32_e32 v106, v32
	v_mov_b32_e32 v107, v32
	v_mov_b32_e32 v108, v32
	v_mov_b32_e32 v109, v32
	v_mov_b32_e32 v110, v32
	v_mov_b32_e32 v111, v32
	v_mov_b32_e32 v120, v32
	v_mov_b32_e32 v121, v32
	v_mov_b32_e32 v122, v32
	v_mov_b32_e32 v123, v32
	v_mov_b32_e32 v124, v32
	v_mov_b32_e32 v125, v32
	v_mov_b32_e32 v126, v32
	v_mov_b32_e32 v127, v32
	v_mov_b32_e32 v136, v32
	v_mov_b32_e32 v137, v32
	v_mov_b32_e32 v138, v32
	v_mov_b32_e32 v139, v32
	v_mov_b32_e32 v140, v32
	v_mov_b32_e32 v141, v32
	v_mov_b32_e32 v142, v32
	v_mov_b32_e32 v143, v32
	v_mov_b32_e32 v152, v32
	v_mov_b32_e32 v153, v32
	v_mov_b32_e32 v154, v32
	v_mov_b32_e32 v155, v32
	v_mov_b32_e32 v156, v32
	v_mov_b32_e32 v157, v32
	v_mov_b32_e32 v158, v32
	v_mov_b32_e32 v159, v32
	v_readfirstlane_b32 s80, v184
	s_lshr_b32 s80, s80, 6
	s_lshl_b32 s81, s2, 3
	s_add_u32 s80, s80, s81
	s_lshl_b32 s80, s80, 12
	v_readlane_b32 s58, v254, 2
	v_readlane_b32 s59, v254, 3
	v_readlane_b32 s60, v254, 38
	v_readlane_b32 s61, v254, 39
	s_add_u32 s58, s58, s80
	s_addc_u32 s59, s59, 0
	s_add_u32 s60, s60, s80
	s_addc_u32 s61, s61, 0
	v_mbcnt_hi_u32_b32 v228, -1, v185
	v_lshlrev_b32_e32 v228, 6, v228
.LBB0_378:
	ds_read_b128 v[16:19], v191
	ds_read_b128 v[20:23], v191 offset:1024
	ds_read_b128 v[24:27], v191 offset:2048
	ds_read_b128 v[28:31], v191 offset:3072
	ds_read_b128 v[0:3], v192
	ds_read_b128 v[4:7], v192 offset:1024
	ds_read_b128 v[8:11], v192 offset:2048
	ds_read_b128 v[12:15], v192 offset:3072
	s_add_u32 s88, s86, 0xfffc0080
	s_addc_u32 s89, s87, -1
	s_cmp_eq_u32 s96, 12
	s_cselect_b32 s91, s69, s89
	s_cselect_b32 s90, s83, s88
	s_cselect_b32 s89, s21, s95
	s_cselect_b32 s88, s93, s94
	v_lshl_add_u64 v[218:219], s[86:87], 0, v[168:169]
	s_add_i32 m0, s22, 0xc000
	ds_read_b128 v[176:179], v193
	ds_read_b128 v[180:183], v193 offset:1024
	ds_read_b128 v[194:197], v193 offset:2048
	ds_read_b128 v[198:201], v193 offset:3072
	ds_read_b128 v[202:205], v193 offset:4096
	ds_read_b128 v[206:209], v193 offset:5120
	ds_read_b128 v[210:213], v193 offset:6144
	ds_read_b128 v[214:217], v193 offset:7168
	global_load_lds_dwordx4 v[218:219], off
	v_lshl_add_u64 v[218:219], s[86:87], 0, v[170:171]
	s_add_i32 m0, s22, 0xe000
	s_nop 0
	global_load_lds_dwordx4 v[218:219], off
	s_waitcnt vmcnt(8)
	s_add_u32 s98, s96, 2
	s_lshr_b32 s98, s98, 1
	s_cmp_ge_u32 s98, 6
	s_cselect_b64 s[72:73], s[60:61], s[58:59]
	s_cselect_b32 s81, 6, 0
	s_sub_u32 s98, s98, s81
	s_lshl_b32 s98, s98, 23
	v_add_u32_e32 v229, s98, v228
	global_load_dword v230, v229, s[72:73]
	s_waitcnt lgkmcnt(0)
	s_barrier
	s_setprio 1
	s_waitcnt lgkmcnt(0)
	v_mfma_scale_f32_16x16x128_f8f6f4 v[156:159], v[16:23], v[176:183], v[156:159], v186, v187 op_sel_hi:[0,0,0]
	v_mfma_scale_f32_16x16x128_f8f6f4 v[152:155], v[24:31], v[176:183], v[152:155], v186, v187 op_sel_hi:[0,0,0]
	v_mfma_scale_f32_16x16x128_f8f6f4 v[140:143], v[16:23], v[194:201], v[140:143], v186, v187 op_sel_hi:[0,0,0]
	v_mfma_scale_f32_16x16x128_f8f6f4 v[136:139], v[24:31], v[194:201], v[136:139], v186, v187 op_sel_hi:[0,0,0]
	v_mfma_scale_f32_16x16x128_f8f6f4 v[124:127], v[16:23], v[202:209], v[124:127], v186, v187 op_sel_hi:[0,0,0]
	v_mfma_scale_f32_16x16x128_f8f6f4 v[120:123], v[24:31], v[202:209], v[120:123], v186, v187 op_sel_hi:[0,0,0]
	v_mfma_scale_f32_16x16x128_f8f6f4 v[108:111], v[16:23], v[210:217], v[108:111], v186, v187 op_sel_hi:[0,0,0]
	v_mfma_scale_f32_16x16x128_f8f6f4 v[104:107], v[24:31], v[210:217], v[104:107], v186, v187 op_sel_hi:[0,0,0]
	s_setprio 0
	s_setprio 1
	v_mfma_scale_f32_16x16x128_f8f6f4 v[148:151], v[0:7], v[176:183], v[148:151], v186, v187 op_sel_hi:[0,0,0]
	v_mfma_scale_f32_16x16x128_f8f6f4 v[144:147], v[8:15], v[176:183], v[144:147], v186, v187 op_sel_hi:[0,0,0]
	v_mfma_scale_f32_16x16x128_f8f6f4 v[132:135], v[0:7], v[194:201], v[132:135], v186, v187 op_sel_hi:[0,0,0]
	v_mfma_scale_f32_16x16x128_f8f6f4 v[128:131], v[8:15], v[194:201], v[128:131], v186, v187 op_sel_hi:[0,0,0]
	v_mfma_scale_f32_16x16x128_f8f6f4 v[116:119], v[0:7], v[202:209], v[116:119], v186, v187 op_sel_hi:[0,0,0]
	v_mfma_scale_f32_16x16x128_f8f6f4 v[112:115], v[8:15], v[202:209], v[112:115], v186, v187 op_sel_hi:[0,0,0]
	v_mfma_scale_f32_16x16x128_f8f6f4 v[100:103], v[0:7], v[210:217], v[100:103], v186, v187 op_sel_hi:[0,0,0]
	v_mfma_scale_f32_16x16x128_f8f6f4 v[96:99], v[8:15], v[210:217], v[96:99], v186, v187 op_sel_hi:[0,0,0]
	s_setprio 0
	s_barrier
	s_add_i32 s97, s67, s19
	v_lshl_add_u64 v[176:177], s[88:89], 0, v[162:163]
	s_mov_b32 m0, s97
	ds_read_b128 v[194:197], v193 offset:16384
	ds_read_b128 v[198:201], v193 offset:17408
	ds_read_b128 v[202:205], v193 offset:18432
	ds_read_b128 v[206:209], v193 offset:19456
	ds_read_b128 v[210:213], v193 offset:20480
	ds_read_b128 v[214:217], v193 offset:21504
	ds_read_b128 v[218:221], v193 offset:22528
	ds_read_b128 v[222:225], v193 offset:23552
	global_load_lds_dwordx4 v[176:177], off
	s_add_i32 m0, s97, 0x2000
	s_add_u32 vcc_lo, s88, 0x40000
	v_lshl_add_u64 v[178:179], s[88:89], 0, v[166:167]
	s_addc_u32 vcc_hi, s89, 0
	s_add_i32 s97, s85, s19
	global_load_lds_dwordx4 v[178:179], off
	v_lshl_add_u64 v[180:181], vcc, 0, v[162:163]
	s_mov_b32 m0, s97
	v_lshl_add_u64 v[182:183], s[90:91], 0, v[164:165]
	global_load_lds_dwordx4 v[180:181], off
	v_lshl_add_u64 v[180:181], vcc, 0, v[166:167]
	s_add_i32 m0, s97, 0x2000
	s_nop 0
	global_load_lds_dwordx4 v[180:181], off
	v_lshl_add_u64 v[180:181], s[90:91], 0, v[160:161]
	s_mov_b32 m0, s22
	s_nop 0
	global_load_lds_dwordx4 v[180:181], off
	s_mov_b32 m0, s23
	s_nop 0
	global_load_lds_dwordx4 v[182:183], off
	s_waitcnt vmcnt(9)
	s_waitcnt lgkmcnt(0)
	s_barrier
	s_setprio 1
	s_waitcnt lgkmcnt(0)
	v_mfma_scale_f32_16x16x128_f8f6f4 v[92:95], v[16:23], v[194:201], v[92:95], v186, v187 op_sel_hi:[0,0,0]
	v_mfma_scale_f32_16x16x128_f8f6f4 v[88:91], v[24:31], v[194:201], v[88:91], v186, v187 op_sel_hi:[0,0,0]
	v_mfma_scale_f32_16x16x128_f8f6f4 v[76:79], v[16:23], v[202:209], v[76:79], v186, v187 op_sel_hi:[0,0,0]
	v_mfma_scale_f32_16x16x128_f8f6f4 v[72:75], v[24:31], v[202:209], v[72:75], v186, v187 op_sel_hi:[0,0,0]
	v_mfma_scale_f32_16x16x128_f8f6f4 v[60:63], v[16:23], v[210:217], v[60:63], v186, v187 op_sel_hi:[0,0,0]
	v_mfma_scale_f32_16x16x128_f8f6f4 v[56:59], v[24:31], v[210:217], v[56:59], v186, v187 op_sel_hi:[0,0,0]
	v_mfma_scale_f32_16x16x128_f8f6f4 v[44:47], v[16:23], v[218:225], v[44:47], v186, v187 op_sel_hi:[0,0,0]
	v_mfma_scale_f32_16x16x128_f8f6f4 v[40:43], v[24:31], v[218:225], v[40:43], v186, v187 op_sel_hi:[0,0,0]
	s_setprio 0
	s_setprio 1
	v_mfma_scale_f32_16x16x128_f8f6f4 v[84:87], v[0:7], v[194:201], v[84:87], v186, v187 op_sel_hi:[0,0,0]
	v_mfma_scale_f32_16x16x128_f8f6f4 v[80:83], v[8:15], v[194:201], v[80:83], v186, v187 op_sel_hi:[0,0,0]
	v_mfma_scale_f32_16x16x128_f8f6f4 v[68:71], v[0:7], v[202:209], v[68:71], v186, v187 op_sel_hi:[0,0,0]
	v_mfma_scale_f32_16x16x128_f8f6f4 v[64:67], v[8:15], v[202:209], v[64:67], v186, v187 op_sel_hi:[0,0,0]
	v_mfma_scale_f32_16x16x128_f8f6f4 v[52:55], v[0:7], v[210:217], v[52:55], v186, v187 op_sel_hi:[0,0,0]
	v_mfma_scale_f32_16x16x128_f8f6f4 v[48:51], v[8:15], v[210:217], v[48:51], v186, v187 op_sel_hi:[0,0,0]
	v_mfma_scale_f32_16x16x128_f8f6f4 v[36:39], v[0:7], v[218:225], v[36:39], v186, v187 op_sel_hi:[0,0,0]
	v_mfma_scale_f32_16x16x128_f8f6f4 v[32:35], v[8:15], v[218:225], v[32:35], v186, v187 op_sel_hi:[0,0,0]
	s_setprio 0
	s_barrier
	s_add_i32 s97, 0, 0x18000
	s_add_i32 vcc_lo, 0, 0x1c000
	v_add_u32_e32 v12, s97, v189
	v_add_u32_e32 v28, vcc_lo, v189
	ds_read_b128 v[0:3], v12
	ds_read_b128 v[4:7], v12 offset:1024
	ds_read_b128 v[8:11], v12 offset:2048
	ds_read_b128 v[12:15], v12 offset:3072
	ds_read_b128 v[16:19], v28
	ds_read_b128 v[20:23], v28 offset:1024
	ds_read_b128 v[24:27], v28 offset:2048
	ds_read_b128 v[28:31], v28 offset:3072
	s_add_u32 s90, s90, 0x40000
	s_addc_u32 s91, s91, 0
	s_mov_b32 m0, s24
	v_lshl_add_u64 v[226:227], s[90:91], 0, v[160:161]
	ds_read_b128 v[194:197], v193 offset:32768
	ds_read_b128 v[198:201], v193 offset:33792
	ds_read_b128 v[202:205], v193 offset:34816
	ds_read_b128 v[206:209], v193 offset:35840
	ds_read_b128 v[210:213], v193 offset:36864
	ds_read_b128 v[214:217], v193 offset:37888
	ds_read_b128 v[218:221], v193 offset:38912
	ds_read_b128 v[222:225], v193 offset:39936
	global_load_lds_dwordx4 v[226:227], off
	v_lshl_add_u64 v[226:227], s[90:91], 0, v[164:165]
	s_mov_b32 m0, s25
	s_nop 0
	global_load_lds_dwordx4 v[226:227], off
	s_waitcnt vmcnt(9)
	s_waitcnt lgkmcnt(0)
	s_barrier
	s_setprio 1
	s_waitcnt lgkmcnt(0)
	v_mfma_scale_f32_16x16x128_f8f6f4 v[156:159], v[0:7], v[194:201], v[156:159], v186, v187 op_sel_hi:[0,0,0]
	v_mfma_scale_f32_16x16x128_f8f6f4 v[152:155], v[8:15], v[194:201], v[152:155], v186, v187 op_sel_hi:[0,0,0]
	v_mfma_scale_f32_16x16x128_f8f6f4 v[140:143], v[0:7], v[202:209], v[140:143], v186, v187 op_sel_hi:[0,0,0]
	v_mfma_scale_f32_16x16x128_f8f6f4 v[136:139], v[8:15], v[202:209], v[136:139], v186, v187 op_sel_hi:[0,0,0]
	v_mfma_scale_f32_16x16x128_f8f6f4 v[124:127], v[0:7], v[210:217], v[124:127], v186, v187 op_sel_hi:[0,0,0]
	v_mfma_scale_f32_16x16x128_f8f6f4 v[120:123], v[8:15], v[210:217], v[120:123], v186, v187 op_sel_hi:[0,0,0]
	v_mfma_scale_f32_16x16x128_f8f6f4 v[108:111], v[0:7], v[218:225], v[108:111], v186, v187 op_sel_hi:[0,0,0]
	v_mfma_scale_f32_16x16x128_f8f6f4 v[104:107], v[8:15], v[218:225], v[104:107], v186, v187 op_sel_hi:[0,0,0]
	s_setprio 0
	s_setprio 1
	v_mfma_scale_f32_16x16x128_f8f6f4 v[148:151], v[16:23], v[194:201], v[148:151], v186, v187 op_sel_hi:[0,0,0]
	v_mfma_scale_f32_16x16x128_f8f6f4 v[144:147], v[24:31], v[194:201], v[144:147], v186, v187 op_sel_hi:[0,0,0]
	v_mfma_scale_f32_16x16x128_f8f6f4 v[132:135], v[16:23], v[202:209], v[132:135], v186, v187 op_sel_hi:[0,0,0]
	v_mfma_scale_f32_16x16x128_f8f6f4 v[128:131], v[24:31], v[202:209], v[128:131], v186, v187 op_sel_hi:[0,0,0]
	v_mfma_scale_f32_16x16x128_f8f6f4 v[116:119], v[16:23], v[210:217], v[116:119], v186, v187 op_sel_hi:[0,0,0]
	v_mfma_scale_f32_16x16x128_f8f6f4 v[112:115], v[24:31], v[210:217], v[112:115], v186, v187 op_sel_hi:[0,0,0]
	v_mfma_scale_f32_16x16x128_f8f6f4 v[100:103], v[16:23], v[218:225], v[100:103], v186, v187 op_sel_hi:[0,0,0]
	v_mfma_scale_f32_16x16x128_f8f6f4 v[96:99], v[24:31], v[218:225], v[96:99], v186, v187 op_sel_hi:[0,0,0]
	s_setprio 0
	s_barrier
	s_add_i32 s90, s97, s19
	v_lshl_add_u64 v[176:177], v[176:177], 0, s[10:11]
	s_mov_b32 m0, s90
	ds_read_b128 v[194:197], v193 offset:49152
	ds_read_b128 v[198:201], v193 offset:50176
	ds_read_b128 v[202:205], v193 offset:51200
	ds_read_b128 v[206:209], v193 offset:52224
	ds_read_b128 v[210:213], v193 offset:53248
	ds_read_b128 v[214:217], v193 offset:54272
	ds_read_b128 v[218:221], v193 offset:55296
	ds_read_b128 v[222:225], v193 offset:56320
	global_load_lds_dwordx4 v[176:177], off
	s_add_i32 m0, s90, 0x2000
	s_add_u32 s88, s88, 0x40080
	v_lshl_add_u64 v[176:177], v[178:179], 0, s[10:11]
	s_addc_u32 s89, s89, 0
	s_add_i32 s90, vcc_lo, s19
	global_load_lds_dwordx4 v[176:177], off
	v_lshl_add_u64 v[176:177], s[88:89], 0, v[162:163]
	s_mov_b32 m0, s90
	s_nop 0
	global_load_lds_dwordx4 v[176:177], off
	v_lshl_add_u64 v[176:177], s[88:89], 0, v[166:167]
	s_add_i32 m0, s90, 0x2000
	s_nop 0
	global_load_lds_dwordx4 v[176:177], off
	v_lshl_add_u64 v[176:177], v[180:181], 0, s[10:11]
	s_mov_b32 m0, s27
	s_nop 0
	global_load_lds_dwordx4 v[176:177], off
	v_lshl_add_u64 v[176:177], v[182:183], 0, s[10:11]
	s_mov_b32 m0, s33
	s_nop 0
	global_load_lds_dwordx4 v[176:177], off
	s_waitcnt vmcnt(8)
	s_waitcnt lgkmcnt(0)
	s_barrier
	s_setprio 1
	s_waitcnt lgkmcnt(0)
	v_mfma_scale_f32_16x16x128_f8f6f4 v[92:95], v[0:7], v[194:201], v[92:95], v186, v187 op_sel_hi:[0,0,0]
	v_mfma_scale_f32_16x16x128_f8f6f4 v[88:91], v[8:15], v[194:201], v[88:91], v186, v187 op_sel_hi:[0,0,0]
	v_mfma_scale_f32_16x16x128_f8f6f4 v[76:79], v[0:7], v[202:209], v[76:79], v186, v187 op_sel_hi:[0,0,0]
	v_mfma_scale_f32_16x16x128_f8f6f4 v[72:75], v[8:15], v[202:209], v[72:75], v186, v187 op_sel_hi:[0,0,0]
	v_mfma_scale_f32_16x16x128_f8f6f4 v[60:63], v[0:7], v[210:217], v[60:63], v186, v187 op_sel_hi:[0,0,0]
	v_mfma_scale_f32_16x16x128_f8f6f4 v[56:59], v[8:15], v[210:217], v[56:59], v186, v187 op_sel_hi:[0,0,0]
	v_mfma_scale_f32_16x16x128_f8f6f4 v[44:47], v[0:7], v[218:225], v[44:47], v186, v187 op_sel_hi:[0,0,0]
	v_mfma_scale_f32_16x16x128_f8f6f4 v[40:43], v[8:15], v[218:225], v[40:43], v186, v187 op_sel_hi:[0,0,0]
	s_setprio 0
	s_setprio 1
	v_mfma_scale_f32_16x16x128_f8f6f4 v[84:87], v[16:23], v[194:201], v[84:87], v186, v187 op_sel_hi:[0,0,0]
	v_mfma_scale_f32_16x16x128_f8f6f4 v[80:83], v[24:31], v[194:201], v[80:83], v186, v187 op_sel_hi:[0,0,0]
	v_mfma_scale_f32_16x16x128_f8f6f4 v[68:71], v[16:23], v[202:209], v[68:71], v186, v187 op_sel_hi:[0,0,0]
	v_mfma_scale_f32_16x16x128_f8f6f4 v[64:67], v[24:31], v[202:209], v[64:67], v186, v187 op_sel_hi:[0,0,0]
	v_mfma_scale_f32_16x16x128_f8f6f4 v[52:55], v[16:23], v[210:217], v[52:55], v186, v187 op_sel_hi:[0,0,0]
	v_mfma_scale_f32_16x16x128_f8f6f4 v[48:51], v[24:31], v[210:217], v[48:51], v186, v187 op_sel_hi:[0,0,0]
	v_mfma_scale_f32_16x16x128_f8f6f4 v[36:39], v[16:23], v[218:225], v[36:39], v186, v187 op_sel_hi:[0,0,0]
	v_mfma_scale_f32_16x16x128_f8f6f4 v[32:35], v[24:31], v[218:225], v[32:35], v186, v187 op_sel_hi:[0,0,0]
	s_setprio 0
	s_barrier
	s_add_i32 s96, s96, 2
	s_add_u32 s86, s86, 0x100
	s_addc_u32 s87, s87, 0
	s_add_u32 s94, s94, 0x100
	s_addc_u32 s95, s95, 0
	s_cmp_gt_u32 s96, 13
	s_cbranch_scc0 .LBB0_378
	s_and_b64 vcc, exec, s[12:13]
	s_cbranch_vccz .LBB0_381
	s_barrier
